# P1 GEMM: first K-iteration after an epilogue waits vmcnt(24) instead of vmcnt(8) (does not drain the epilogue stores)
# baseline (speedup 1.0000x reference)
.LBB0_7:
	s_or_b64 exec, exec, s[2:3]
	s_load_dwordx16 s[4:19], s[0:1], 0x40
	v_mov_b32_e32 v162, v0
	s_waitcnt lgkmcnt(0)
	v_writelane_b32 v245, s4, 9
	s_nop 1
	v_writelane_b32 v245, s5, 10
	v_writelane_b32 v245, s6, 11
	v_writelane_b32 v245, s7, 12
	v_writelane_b32 v245, s8, 13
	v_writelane_b32 v245, s9, 14
	v_writelane_b32 v245, s10, 15
	v_writelane_b32 v245, s11, 16
	v_writelane_b32 v245, s12, 17
	v_writelane_b32 v245, s13, 18
	v_writelane_b32 v245, s14, 19
	v_writelane_b32 v245, s15, 20
	v_writelane_b32 v245, s16, 21
	v_writelane_b32 v245, s17, 22
	v_writelane_b32 v245, s18, 23
	v_writelane_b32 v245, s19, 24
	s_load_dwordx16 s[4:19], s[0:1], 0x80
	s_waitcnt lgkmcnt(0)
	v_writelane_b32 v245, s4, 25
	s_nop 1
	v_writelane_b32 v245, s5, 26
	v_writelane_b32 v245, s6, 27
	v_writelane_b32 v245, s7, 28
	v_writelane_b32 v245, s8, 29
	v_writelane_b32 v245, s9, 30
	v_writelane_b32 v245, s10, 31
	v_writelane_b32 v245, s11, 32
	v_writelane_b32 v245, s12, 33
	v_writelane_b32 v245, s13, 34
	v_writelane_b32 v245, s14, 35
	v_writelane_b32 v245, s15, 36
	v_writelane_b32 v245, s16, 37
	v_writelane_b32 v245, s17, 38
	v_writelane_b32 v245, s18, 39
	v_writelane_b32 v245, s19, 40
	s_nop 0
	v_readlane_b32 s0, v245, 2
	v_readlane_b32 s1, v245, 3
	s_mov_b64 s[4:5], s[0:1]
	s_cmp_lt_i32 s4, 1
	v_readlane_b32 s2, v245, 4
	v_readlane_b32 s3, v245, 5
	s_cselect_b64 s[0:1], -1, 0
	s_cmp_gt_i32 s5, 0
	s_cselect_b64 s[2:3], -1, 0
	s_and_b64 s[0:1], s[0:1], s[2:3]
	s_andn2_b64 vcc, exec, s[0:1]
	s_cbranch_vccnz .LBB0_135
	v_mov_b32_e32 v162, v0
	s_movk_i32 s0, 0x2000
	s_nop 0
	v_readfirstlane_b32 s8, v162
	v_cmp_gt_i32_e32 vcc, s0, v162
	v_and_b32_e32 v1, 7, v162
	s_and_saveexec_b64 s[0:1], vcc
	s_cbranch_execz .LBB0_20
	v_max_i32_e32 v2, 0x1e00, v162
	v_sub_u32_e32 v2, v2, v162
	s_movk_i32 s2, 0x1ff
	v_add_u32_e32 v2, 0x1ff, v2
	v_mov_b32_e32 v4, 0
	v_cmp_lt_u32_e32 vcc, s2, v2
	s_mov_b64 s[4:5], -1
	v_mov_b32_e32 v6, v162
	s_and_saveexec_b64 s[2:3], vcc
	s_cbranch_execz .LBB0_17
	v_lshrrev_b32_e32 v8, 9, v2
	v_add_u32_e32 v163, 0x200, v162
	v_add_u32_e32 v9, -1, v8
	v_cmp_lt_u32_e32 vcc, 1, v9
	v_mov_b64_e32 v[2:3], v[162:163]
	s_and_saveexec_b64 s[4:5], vcc
	s_cbranch_execz .LBB0_14
	v_lshrrev_b32_e32 v2, 1, v9
	v_add_u32_e32 v2, 1, v2
	v_readlane_b32 s12, v245, 9
	v_and_b32_e32 v10, -2, v2
	v_lshl_add_u32 v2, v162, 2, 0
	v_readlane_b32 s18, v245, 15
	v_readlane_b32 s19, v245, 16
	s_mov_b32 s9, 0
	v_add_u32_e32 v11, 0x19800, v2
	s_mov_b64 s[6:7], 0
	s_mov_b32 s10, 0x8020
	v_mov_b64_e32 v[4:5], s[18:19]
	v_lshlrev_b32_e32 v6, 2, v1
	v_mov_b32_e32 v7, 0
	s_movk_i32 s11, 0x4000
	v_mov_b64_e32 v[2:3], v[162:163]
	v_readlane_b32 s13, v245, 10
	v_readlane_b32 s14, v245, 11
	v_readlane_b32 s15, v245, 12
	v_readlane_b32 s16, v245, 13
	v_readlane_b32 s17, v245, 14
	v_readlane_b32 s20, v245, 17
	v_readlane_b32 s21, v245, 18
	v_readlane_b32 s22, v245, 19
	v_readlane_b32 s23, v245, 20
	v_readlane_b32 s24, v245, 21
	v_readlane_b32 s25, v245, 22
	v_readlane_b32 s26, v245, 23
	v_readlane_b32 s27, v245, 24
.LBB0_12:
	v_ashrrev_i32_e32 v12, 3, v2
	v_mad_i64_i32 v[12:13], s[12:13], v12, s10, v[4:5]
	v_ashrrev_i32_e32 v14, 3, v3
	v_lshl_add_u64 v[12:13], v[12:13], 0, v[6:7]
	v_add_u32_e32 v16, 0x400, v2
	v_mad_i64_i32 v[14:15], s[12:13], v14, s10, v[4:5]
	v_add_co_u32_e32 v12, vcc, 0x4000, v12
	v_add_u32_e32 v17, 0x400, v3
	v_ashrrev_i32_e32 v16, 3, v16
	v_lshl_add_u64 v[14:15], v[14:15], 0, v[6:7]
	v_addc_co_u32_e32 v13, vcc, 0, v13, vcc
	v_ashrrev_i32_e32 v18, 3, v17
	v_mad_i64_i32 v[16:17], s[12:13], v16, s10, v[4:5]
	v_add_co_u32_e32 v14, vcc, 0x4000, v14
	v_lshl_add_u64 v[16:17], v[16:17], 0, v[6:7]
	s_nop 0
	v_addc_co_u32_e32 v15, vcc, 0, v15, vcc
	v_mad_i64_i32 v[18:19], s[12:13], v18, s10, v[4:5]
	v_add_co_u32_e32 v16, vcc, s11, v16
	v_lshl_add_u64 v[18:19], v[18:19], 0, v[6:7]
	s_nop 0
	v_addc_co_u32_e32 v17, vcc, 0, v17, vcc
	global_load_dword v20, v[12:13], off
	s_nop 0
	global_load_dword v14, v[14:15], off
	v_add_co_u32_e32 v12, vcc, s11, v18
	v_add_u32_e32 v10, -2, v10
	s_nop 0
	v_addc_co_u32_e32 v13, vcc, 0, v19, vcc
	global_load_dword v15, v[16:17], off
	s_nop 0
	global_load_dword v13, v[12:13], off
	v_add_u32_e32 v16, 0xffffe800, v11
	s_add_i32 s9, s9, 4
	v_cmp_eq_u32_e32 vcc, 0, v10
	v_add_u32_e32 v17, 0xfffff000, v11
	v_add_u32_e32 v18, 0xfffff800, v11
	v_add_u32_e32 v3, 0x800, v3
	v_add_u32_e32 v2, 0x800, v2
	v_mov_b32_e32 v12, s9
	s_or_b64 s[6:7], vcc, s[6:7]
	s_waitcnt vmcnt(3)
	ds_write_b32 v16, v20
	s_waitcnt vmcnt(2)
	ds_write_b32 v17, v14
	s_waitcnt vmcnt(1)
	ds_write_b32 v18, v15
	s_waitcnt vmcnt(0)
	ds_write_b32 v11, v13
	v_add_u32_e32 v11, 0x2000, v11
	s_andn2_b64 exec, exec, s[6:7]
	s_cbranch_execnz .LBB0_12
	s_or_b64 exec, exec, s[6:7]
	v_lshlrev_b32_e32 v4, 9, v12
.LBB0_14:
	s_or_b64 exec, exec, s[4:5]
	v_and_b32_e32 v5, 2, v9
	v_cmp_eq_u32_e32 vcc, 0, v5
	s_and_saveexec_b64 s[4:5], vcc
	s_cbranch_execz .LBB0_16
	v_readlane_b32 s12, v245, 9
	v_readlane_b32 s18, v245, 15
	v_readlane_b32 s19, v245, 16
	v_ashrrev_i32_e32 v5, 3, v3
	v_ashrrev_i32_e32 v6, 3, v2
	s_mov_b32 s9, 0x8020
	v_mov_b64_e32 v[2:3], s[18:19]
	v_mad_i64_i32 v[6:7], s[6:7], v6, s9, v[2:3]
	v_lshlrev_b32_e32 v10, 2, v1
	v_mov_b32_e32 v11, 0
	v_lshl_add_u64 v[6:7], v[6:7], 0, v[10:11]
	v_mad_i64_i32 v[2:3], s[6:7], v5, s9, v[2:3]
	v_add_co_u32_e32 v6, vcc, 0x4000, v6
	v_lshl_add_u64 v[2:3], v[2:3], 0, v[10:11]
	s_nop 0
	v_addc_co_u32_e32 v7, vcc, 0, v7, vcc
	v_add_co_u32_e32 v2, vcc, 0x4000, v2
	v_readlane_b32 s13, v245, 10
	s_nop 0
	v_addc_co_u32_e32 v3, vcc, 0, v3, vcc
	global_load_dword v5, v[6:7], off
	s_nop 0
	global_load_dword v2, v[2:3], off
	v_add_u32_e32 v3, v162, v4
	v_lshl_add_u32 v3, v3, 2, 0
	v_add_u32_e32 v3, 0x18000, v3
	v_readlane_b32 s14, v245, 11
	v_readlane_b32 s15, v245, 12
	v_readlane_b32 s16, v245, 13
	v_readlane_b32 s17, v245, 14
	v_readlane_b32 s20, v245, 17
	v_readlane_b32 s21, v245, 18
	v_readlane_b32 s22, v245, 19
	v_readlane_b32 s23, v245, 20
	v_readlane_b32 s24, v245, 21
	v_readlane_b32 s25, v245, 22
	v_readlane_b32 s26, v245, 23
	v_readlane_b32 s27, v245, 24
	s_waitcnt vmcnt(0)
	ds_write2st64_b32 v3, v5, v2 offset1:8
.LBB0_16:
	s_or_b64 exec, exec, s[4:5]
	v_add_u32_e32 v2, 1, v8
	v_and_b32_e32 v3, 0xfffffe, v2
	v_cmp_ne_u32_e32 vcc, v2, v3
	v_lshl_add_u32 v6, v3, 9, v162
	s_orn2_b64 s[4:5], vcc, exec
.LBB0_17:
	s_or_b64 exec, exec, s[2:3]
	s_and_b64 exec, exec, s[4:5]
	s_cbranch_execz .LBB0_20
	v_readlane_b32 s12, v245, 9
	v_lshl_add_u32 v2, v6, 2, 0
	v_readlane_b32 s18, v245, 15
	v_readlane_b32 s19, v245, 16
	v_add_u32_e32 v7, 0x18000, v2
	s_mov_b64 s[2:3], 0
	s_mov_b32 s4, 0x8020
	v_mov_b64_e32 v[2:3], s[18:19]
	v_lshlrev_b32_e32 v4, 2, v1
	v_mov_b32_e32 v5, 0
	s_movk_i32 s5, 0x1dff
	v_readlane_b32 s13, v245, 10
	v_readlane_b32 s14, v245, 11
	v_readlane_b32 s15, v245, 12
	v_readlane_b32 s16, v245, 13
	v_readlane_b32 s17, v245, 14
	v_readlane_b32 s20, v245, 17
	v_readlane_b32 s21, v245, 18
	v_readlane_b32 s22, v245, 19
	v_readlane_b32 s23, v245, 20
	v_readlane_b32 s24, v245, 21
	v_readlane_b32 s25, v245, 22
	v_readlane_b32 s26, v245, 23
	v_readlane_b32 s27, v245, 24
.LBB0_19:
	v_ashrrev_i32_e32 v8, 3, v6
	v_mad_i64_i32 v[8:9], s[6:7], v8, s4, v[2:3]
	v_lshl_add_u64 v[8:9], v[8:9], 0, v[4:5]
	v_add_co_u32_e32 v8, vcc, 0x4000, v8
	s_nop 1
	v_addc_co_u32_e32 v9, vcc, 0, v9, vcc
	global_load_dword v8, v[8:9], off
	v_add_u32_e32 v9, 0x200, v6
	v_cmp_lt_i32_e32 vcc, s5, v6
	s_or_b64 s[2:3], vcc, s[2:3]
	v_mov_b32_e32 v6, v9
	s_waitcnt vmcnt(0)
	ds_write_b32 v7, v8
	v_add_u32_e32 v7, 0x800, v7
	s_andn2_b64 exec, exec, s[2:3]
	s_cbranch_execnz .LBB0_19
.LBB0_20:
	s_or_b64 exec, exec, s[0:1]
	s_ashr_i32 s33, s8, 6
	s_lshl_b32 s0, s92, 3
	s_add_i32 s22, s33, s0
	s_cmpk_gt_i32 s22, 0x3fff
	s_waitcnt lgkmcnt(0)
	s_barrier
	s_cbranch_scc0 .LBB0_22
	s_add_i32 s0, s22, 0xffffc000
	s_mov_b32 s1, 0
	s_lshl_b64 s[0:1], s[0:1], 12
	s_add_u32 s0, s70, s0
	s_addc_u32 s1, s71, s1
	s_cmpk_lt_u32 s22, 0x4080
	s_cselect_b32 s1, s1, 0
	s_cselect_b32 s0, s0, 0
	s_cbranch_execz .LBB0_23
	s_branch .LBB0_24

.LBB0_243:
	s_and_b64 vcc, exec, s[0:1]
	s_cbranch_vccz .LBB0_477
	s_mov_b32 s99, 0
	v_readfirstlane_b32 s2, v0
	s_cmp_lt_i32 s85, 32
	s_mov_b32 s12, 64
	s_cbranch_scc1 .LBB0_246
	s_sub_i32 s0, s85, 32
	s_lshl_b32 s3, s85, 8
	s_lshr_b32 s1, s0, 3
	s_and_b32 s3, s3, 0x700
	s_add_i32 s3, s3, s1
	s_bfe_u32 s1, s3, 0x80008
	s_lshl_b32 s1, s1, 3
	s_bfe_u32 s3, s0, 0x30003
	s_or_b32 s12, s1, s3
	s_lshr_b32 s86, s0, 6

.LBB0_250:
	s_mov_b32 s99, 1
	s_andn2_b64 vcc, exec, s[0:1]
	s_mov_b32 s86, s64
	s_mov_b32 s12, s26
	s_mov_b64 s[4:5], s[88:89]
	s_mov_b64 s[0:1], s[68:69]
	s_cbranch_vccz .LBB0_476

.LBB0_260:
	ds_read_b128 v[130:133], v166
	ds_read_b128 v[134:137], v166 offset:1024
	ds_read_b128 v[152:155], v166 offset:2048
	ds_read_b128 v[156:159], v166 offset:3072
	ds_read_b128 v[176:179], v167
	ds_read_b128 v[180:183], v167 offset:1024
	ds_read_b128 v[184:187], v167 offset:2048
	ds_read_b128 v[188:191], v167 offset:3072
	s_add_u32 s4, s0, 0xfffc0080
	s_addc_u32 s5, s1, -1
	s_cmp_eq_u32 s23, 12
	s_cselect_b32 s7, s8, s5
	s_cselect_b32 s6, s9, s4
	s_cselect_b32 s5, s10, s22
	s_cselect_b32 s4, s11, s13
	v_lshl_add_u64 v[160:161], s[0:1], 0, v[148:149]
	s_add_i32 m0, s29, 0xc000
	ds_read_b128 v[192:195], v168
	ds_read_b128 v[196:199], v168 offset:1024
	ds_read_b128 v[200:203], v168 offset:2048
	ds_read_b128 v[204:207], v168 offset:3072
	ds_read_b128 v[208:211], v168 offset:4096
	ds_read_b128 v[212:215], v168 offset:5120
	ds_read_b128 v[216:219], v168 offset:6144
	ds_read_b128 v[220:223], v168 offset:7168
	global_load_lds_dwordx4 v[160:161], off
	v_lshl_add_u64 v[160:161], s[0:1], 0, v[150:151]
	s_add_i32 m0, s29, 0xe000
	s_nop 0
	global_load_lds_dwordx4 v[160:161], off
	s_cmp_lg_u32 s99, 0
	s_cbranch_scc1 .Lmy_w1_relaxed
	s_waitcnt vmcnt(8)
	s_branch .Lmy_w1_done
.Lmy_w1_relaxed:
	s_waitcnt vmcnt(24)
.Lmy_w1_done:
	s_waitcnt lgkmcnt(0)
	s_barrier
	s_setprio 1
	s_waitcnt lgkmcnt(0)
	v_mfma_f32_16x16x32_bf16 v[126:129], v[130:133], v[192:195], v[126:129]
	v_mfma_f32_16x16x32_bf16 v[122:125], v[152:155], v[192:195], v[122:125]
	v_mfma_f32_16x16x32_bf16 v[114:117], v[130:133], v[200:203], v[114:117]
	v_mfma_f32_16x16x32_bf16 v[106:109], v[152:155], v[200:203], v[106:109]
	v_mfma_f32_16x16x32_bf16 v[98:101], v[130:133], v[208:211], v[98:101]
	v_mfma_f32_16x16x32_bf16 v[90:93], v[152:155], v[208:211], v[90:93]
	v_mfma_f32_16x16x32_bf16 v[82:85], v[130:133], v[216:219], v[82:85]
	v_mfma_f32_16x16x32_bf16 v[74:77], v[152:155], v[216:219], v[74:77]
	v_mfma_f32_16x16x32_bf16 v[126:129], v[134:137], v[196:199], v[126:129]
	v_mfma_f32_16x16x32_bf16 v[122:125], v[156:159], v[196:199], v[122:125]
	v_mfma_f32_16x16x32_bf16 v[114:117], v[134:137], v[204:207], v[114:117]
	v_mfma_f32_16x16x32_bf16 v[106:109], v[156:159], v[204:207], v[106:109]
	v_mfma_f32_16x16x32_bf16 v[98:101], v[134:137], v[212:215], v[98:101]
	v_mfma_f32_16x16x32_bf16 v[90:93], v[156:159], v[212:215], v[90:93]
	v_mfma_f32_16x16x32_bf16 v[82:85], v[134:137], v[220:223], v[82:85]
	v_mfma_f32_16x16x32_bf16 v[74:77], v[156:159], v[220:223], v[74:77]
	s_setprio 0
	s_setprio 1
	v_mfma_f32_16x16x32_bf16 v[118:121], v[176:179], v[192:195], v[118:121]
	v_mfma_f32_16x16x32_bf16 v[110:113], v[184:187], v[192:195], v[110:113]
	v_mfma_f32_16x16x32_bf16 v[102:105], v[176:179], v[200:203], v[102:105]
	v_mfma_f32_16x16x32_bf16 v[94:97], v[184:187], v[200:203], v[94:97]
	v_mfma_f32_16x16x32_bf16 v[86:89], v[176:179], v[208:211], v[86:89]
	v_mfma_f32_16x16x32_bf16 v[78:81], v[184:187], v[208:211], v[78:81]
	v_mfma_f32_16x16x32_bf16 v[70:73], v[176:179], v[216:219], v[70:73]
	v_mfma_f32_16x16x32_bf16 v[66:69], v[184:187], v[216:219], v[66:69]
	v_mfma_f32_16x16x32_bf16 v[118:121], v[180:183], v[196:199], v[118:121]
	v_mfma_f32_16x16x32_bf16 v[110:113], v[188:191], v[196:199], v[110:113]
	v_mfma_f32_16x16x32_bf16 v[102:105], v[180:183], v[204:207], v[102:105]
	v_mfma_f32_16x16x32_bf16 v[94:97], v[188:191], v[204:207], v[94:97]
	v_mfma_f32_16x16x32_bf16 v[86:89], v[180:183], v[212:215], v[86:89]
	v_mfma_f32_16x16x32_bf16 v[78:81], v[188:191], v[212:215], v[78:81]
	v_mfma_f32_16x16x32_bf16 v[70:73], v[180:183], v[220:223], v[70:73]
	v_mfma_f32_16x16x32_bf16 v[66:69], v[188:191], v[220:223], v[66:69]
	s_setprio 0
	s_barrier
	s_add_i32 s24, s84, s28
	v_lshl_add_u64 v[160:161], s[4:5], 0, v[140:141]
	s_mov_b32 m0, s24
	ds_read_b128 v[192:195], v168 offset:16384
	ds_read_b128 v[196:199], v168 offset:17408
	ds_read_b128 v[200:203], v168 offset:18432
	ds_read_b128 v[204:207], v168 offset:19456
	ds_read_b128 v[208:211], v168 offset:20480
	ds_read_b128 v[212:215], v168 offset:21504
	ds_read_b128 v[216:219], v168 offset:22528
	ds_read_b128 v[220:223], v168 offset:23552
	global_load_lds_dwordx4 v[160:161], off
	s_add_i32 m0, s24, 0x2000
	s_add_u32 s24, s4, 0x40000
	v_lshl_add_u64 v[224:225], s[4:5], 0, v[144:145]
	s_addc_u32 s25, s5, 0
	s_add_i32 s33, s85, s28
	global_load_lds_dwordx4 v[224:225], off
	v_lshl_add_u64 v[226:227], s[24:25], 0, v[140:141]
	s_mov_b32 m0, s33
	v_lshl_add_u64 v[228:229], s[6:7], 0, v[142:143]
	global_load_lds_dwordx4 v[226:227], off
	v_lshl_add_u64 v[226:227], s[24:25], 0, v[144:145]
	s_add_i32 m0, s33, 0x2000
	s_nop 0
	global_load_lds_dwordx4 v[226:227], off
	v_lshl_add_u64 v[226:227], s[6:7], 0, v[138:139]
	s_mov_b32 m0, s29
	s_nop 0
	global_load_lds_dwordx4 v[226:227], off
	s_mov_b32 m0, s31
	s_nop 0
	global_load_lds_dwordx4 v[228:229], off
	s_cmp_lg_u32 s99, 0
	s_cbranch_scc1 .Lmy_w2_relaxed
	s_waitcnt vmcnt(8)
	s_branch .Lmy_w2_done

.Lmy_w2_done:
	s_mov_b32 s99, 0
	s_waitcnt lgkmcnt(0)
	s_barrier
	s_setprio 1
	s_waitcnt lgkmcnt(0)
	v_mfma_f32_16x16x32_bf16 v[62:65], v[130:133], v[192:195], v[62:65]
	v_mfma_f32_16x16x32_bf16 v[58:61], v[152:155], v[192:195], v[58:61]
	v_mfma_f32_16x16x32_bf16 v[50:53], v[130:133], v[200:203], v[50:53]
	v_mfma_f32_16x16x32_bf16 v[42:45], v[152:155], v[200:203], v[42:45]
	v_mfma_f32_16x16x32_bf16 v[34:37], v[130:133], v[208:211], v[34:37]
	v_mfma_f32_16x16x32_bf16 v[26:29], v[152:155], v[208:211], v[26:29]
	v_mfma_f32_16x16x32_bf16 v[18:21], v[130:133], v[216:219], v[18:21]
	v_mfma_f32_16x16x32_bf16 v[10:13], v[152:155], v[216:219], v[10:13]
	v_mfma_f32_16x16x32_bf16 v[62:65], v[134:137], v[196:199], v[62:65]
	v_mfma_f32_16x16x32_bf16 v[58:61], v[156:159], v[196:199], v[58:61]
	v_mfma_f32_16x16x32_bf16 v[50:53], v[134:137], v[204:207], v[50:53]
	v_mfma_f32_16x16x32_bf16 v[42:45], v[156:159], v[204:207], v[42:45]
	v_mfma_f32_16x16x32_bf16 v[34:37], v[134:137], v[212:215], v[34:37]
	v_mfma_f32_16x16x32_bf16 v[26:29], v[156:159], v[212:215], v[26:29]
	v_mfma_f32_16x16x32_bf16 v[18:21], v[134:137], v[220:223], v[18:21]
	v_mfma_f32_16x16x32_bf16 v[10:13], v[156:159], v[220:223], v[10:13]
	s_setprio 0
	s_setprio 1
	v_mfma_f32_16x16x32_bf16 v[54:57], v[176:179], v[192:195], v[54:57]
	v_mfma_f32_16x16x32_bf16 v[46:49], v[184:187], v[192:195], v[46:49]
	v_mfma_f32_16x16x32_bf16 v[38:41], v[176:179], v[200:203], v[38:41]
	v_mfma_f32_16x16x32_bf16 v[30:33], v[184:187], v[200:203], v[30:33]
	v_mfma_f32_16x16x32_bf16 v[22:25], v[176:179], v[208:211], v[22:25]
	v_mfma_f32_16x16x32_bf16 v[14:17], v[184:187], v[208:211], v[14:17]
	v_mfma_f32_16x16x32_bf16 v[6:9], v[176:179], v[216:219], v[6:9]
	v_mfma_f32_16x16x32_bf16 v[2:5], v[184:187], v[216:219], v[2:5]
	v_mfma_f32_16x16x32_bf16 v[54:57], v[180:183], v[196:199], v[54:57]
	v_mfma_f32_16x16x32_bf16 v[46:49], v[188:191], v[196:199], v[46:49]
	v_mfma_f32_16x16x32_bf16 v[38:41], v[180:183], v[204:207], v[38:41]
	v_mfma_f32_16x16x32_bf16 v[30:33], v[188:191], v[204:207], v[30:33]
	v_mfma_f32_16x16x32_bf16 v[22:25], v[180:183], v[212:215], v[22:25]
	v_mfma_f32_16x16x32_bf16 v[14:17], v[188:191], v[212:215], v[14:17]
	v_mfma_f32_16x16x32_bf16 v[6:9], v[180:183], v[220:223], v[6:9]
	v_mfma_f32_16x16x32_bf16 v[2:5], v[188:191], v[220:223], v[2:5]
	s_setprio 0
	s_barrier
	s_add_i32 s24, 0, 0x18000
	v_add_u32_e32 v146, s24, v162
	s_add_i32 s25, 0, 0x1c000
	ds_read_b128 v[130:133], v146
	ds_read_b128 v[134:137], v146 offset:1024
	ds_read_b128 v[152:155], v146 offset:2048
	ds_read_b128 v[156:159], v146 offset:3072
	v_add_u32_e32 v146, s25, v162
	ds_read_b128 v[176:179], v146
	ds_read_b128 v[180:183], v146 offset:1024
	ds_read_b128 v[184:187], v146 offset:2048
	ds_read_b128 v[188:191], v146 offset:3072
	s_add_u32 s6, s6, 0x40000
	s_addc_u32 s7, s7, 0
	s_mov_b32 m0, s36
	v_lshl_add_u64 v[230:231], s[6:7], 0, v[138:139]
	ds_read_b128 v[192:195], v168 offset:32768
	ds_read_b128 v[196:199], v168 offset:33792
	ds_read_b128 v[200:203], v168 offset:34816
	ds_read_b128 v[204:207], v168 offset:35840
	ds_read_b128 v[208:211], v168 offset:36864
	ds_read_b128 v[212:215], v168 offset:37888
	ds_read_b128 v[216:219], v168 offset:38912
	ds_read_b128 v[220:223], v168 offset:39936
	global_load_lds_dwordx4 v[230:231], off
	v_lshl_add_u64 v[230:231], s[6:7], 0, v[142:143]
	s_mov_b32 m0, s37
	s_nop 0
	global_load_lds_dwordx4 v[230:231], off
	s_waitcnt vmcnt(8)
	s_waitcnt lgkmcnt(0)
	s_barrier
	s_setprio 1
	s_waitcnt lgkmcnt(0)
	v_mfma_f32_16x16x32_bf16 v[126:129], v[130:133], v[192:195], v[126:129]
	v_mfma_f32_16x16x32_bf16 v[122:125], v[152:155], v[192:195], v[122:125]
	v_mfma_f32_16x16x32_bf16 v[114:117], v[130:133], v[200:203], v[114:117]
	v_mfma_f32_16x16x32_bf16 v[106:109], v[152:155], v[200:203], v[106:109]
	v_mfma_f32_16x16x32_bf16 v[98:101], v[130:133], v[208:211], v[98:101]
	v_mfma_f32_16x16x32_bf16 v[90:93], v[152:155], v[208:211], v[90:93]
	v_mfma_f32_16x16x32_bf16 v[82:85], v[130:133], v[216:219], v[82:85]
	v_mfma_f32_16x16x32_bf16 v[74:77], v[152:155], v[216:219], v[74:77]
	v_mfma_f32_16x16x32_bf16 v[126:129], v[134:137], v[196:199], v[126:129]
	v_mfma_f32_16x16x32_bf16 v[122:125], v[156:159], v[196:199], v[122:125]
	v_mfma_f32_16x16x32_bf16 v[114:117], v[134:137], v[204:207], v[114:117]
	v_mfma_f32_16x16x32_bf16 v[106:109], v[156:159], v[204:207], v[106:109]
	v_mfma_f32_16x16x32_bf16 v[98:101], v[134:137], v[212:215], v[98:101]
	v_mfma_f32_16x16x32_bf16 v[90:93], v[156:159], v[212:215], v[90:93]
	v_mfma_f32_16x16x32_bf16 v[82:85], v[134:137], v[220:223], v[82:85]
	v_mfma_f32_16x16x32_bf16 v[74:77], v[156:159], v[220:223], v[74:77]
	s_setprio 0
	s_setprio 1
	v_mfma_f32_16x16x32_bf16 v[118:121], v[176:179], v[192:195], v[118:121]
	v_mfma_f32_16x16x32_bf16 v[110:113], v[184:187], v[192:195], v[110:113]
	v_mfma_f32_16x16x32_bf16 v[102:105], v[176:179], v[200:203], v[102:105]
	v_mfma_f32_16x16x32_bf16 v[94:97], v[184:187], v[200:203], v[94:97]
	v_mfma_f32_16x16x32_bf16 v[86:89], v[176:179], v[208:211], v[86:89]
	v_mfma_f32_16x16x32_bf16 v[78:81], v[184:187], v[208:211], v[78:81]
	v_mfma_f32_16x16x32_bf16 v[70:73], v[176:179], v[216:219], v[70:73]
	v_mfma_f32_16x16x32_bf16 v[66:69], v[184:187], v[216:219], v[66:69]
	v_mfma_f32_16x16x32_bf16 v[118:121], v[180:183], v[196:199], v[118:121]
	v_mfma_f32_16x16x32_bf16 v[110:113], v[188:191], v[196:199], v[110:113]
	v_mfma_f32_16x16x32_bf16 v[102:105], v[180:183], v[204:207], v[102:105]
	v_mfma_f32_16x16x32_bf16 v[94:97], v[188:191], v[204:207], v[94:97]
	v_mfma_f32_16x16x32_bf16 v[86:89], v[180:183], v[212:215], v[86:89]
	v_mfma_f32_16x16x32_bf16 v[78:81], v[188:191], v[212:215], v[78:81]
	v_mfma_f32_16x16x32_bf16 v[70:73], v[180:183], v[220:223], v[70:73]
	v_mfma_f32_16x16x32_bf16 v[66:69], v[188:191], v[220:223], v[66:69]
	s_setprio 0
	s_barrier
	s_add_i32 s6, s24, s28
	v_lshl_add_u64 v[160:161], v[160:161], 0, s[18:19]
	s_mov_b32 m0, s6
	ds_read_b128 v[192:195], v168 offset:49152
	ds_read_b128 v[196:199], v168 offset:50176
	ds_read_b128 v[200:203], v168 offset:51200
	ds_read_b128 v[204:207], v168 offset:52224
	ds_read_b128 v[208:211], v168 offset:53248
	ds_read_b128 v[212:215], v168 offset:54272
	ds_read_b128 v[216:219], v168 offset:55296
	ds_read_b128 v[220:223], v168 offset:56320
	global_load_lds_dwordx4 v[160:161], off
	s_add_i32 m0, s6, 0x2000
	s_add_u32 s4, s4, 0x40080
	v_lshl_add_u64 v[160:161], v[224:225], 0, s[18:19]
	s_addc_u32 s5, s5, 0
	s_add_i32 s6, s25, s28
	global_load_lds_dwordx4 v[160:161], off
	v_lshl_add_u64 v[160:161], s[4:5], 0, v[140:141]
	s_mov_b32 m0, s6
	s_nop 0
	global_load_lds_dwordx4 v[160:161], off
	v_lshl_add_u64 v[160:161], s[4:5], 0, v[144:145]
	s_add_i32 m0, s6, 0x2000
	s_nop 0
	global_load_lds_dwordx4 v[160:161], off
	v_lshl_add_u64 v[160:161], v[226:227], 0, s[18:19]
	s_mov_b32 m0, s41
	s_nop 0
	global_load_lds_dwordx4 v[160:161], off
	v_lshl_add_u64 v[160:161], v[228:229], 0, s[18:19]
	s_mov_b32 m0, s46
	s_nop 0
	global_load_lds_dwordx4 v[160:161], off
	s_waitcnt vmcnt(8)
	s_waitcnt lgkmcnt(0)
	s_barrier
	s_setprio 1
	s_waitcnt lgkmcnt(0)
	v_mfma_f32_16x16x32_bf16 v[62:65], v[130:133], v[192:195], v[62:65]
	v_mfma_f32_16x16x32_bf16 v[58:61], v[152:155], v[192:195], v[58:61]
	v_mfma_f32_16x16x32_bf16 v[50:53], v[130:133], v[200:203], v[50:53]
	v_mfma_f32_16x16x32_bf16 v[42:45], v[152:155], v[200:203], v[42:45]
	v_mfma_f32_16x16x32_bf16 v[34:37], v[130:133], v[208:211], v[34:37]
	v_mfma_f32_16x16x32_bf16 v[26:29], v[152:155], v[208:211], v[26:29]
	v_mfma_f32_16x16x32_bf16 v[18:21], v[130:133], v[216:219], v[18:21]
	v_mfma_f32_16x16x32_bf16 v[10:13], v[152:155], v[216:219], v[10:13]
	v_mfma_f32_16x16x32_bf16 v[62:65], v[134:137], v[196:199], v[62:65]
	v_mfma_f32_16x16x32_bf16 v[58:61], v[156:159], v[196:199], v[58:61]
	v_mfma_f32_16x16x32_bf16 v[50:53], v[134:137], v[204:207], v[50:53]
	v_mfma_f32_16x16x32_bf16 v[42:45], v[156:159], v[204:207], v[42:45]
	v_mfma_f32_16x16x32_bf16 v[34:37], v[134:137], v[212:215], v[34:37]
	v_mfma_f32_16x16x32_bf16 v[26:29], v[156:159], v[212:215], v[26:29]
	v_mfma_f32_16x16x32_bf16 v[18:21], v[134:137], v[220:223], v[18:21]
	v_mfma_f32_16x16x32_bf16 v[10:13], v[156:159], v[220:223], v[10:13]
	s_setprio 0
	s_setprio 1
	v_mfma_f32_16x16x32_bf16 v[54:57], v[176:179], v[192:195], v[54:57]
	v_mfma_f32_16x16x32_bf16 v[46:49], v[184:187], v[192:195], v[46:49]
	v_mfma_f32_16x16x32_bf16 v[38:41], v[176:179], v[200:203], v[38:41]
	v_mfma_f32_16x16x32_bf16 v[30:33], v[184:187], v[200:203], v[30:33]
	v_mfma_f32_16x16x32_bf16 v[22:25], v[176:179], v[208:211], v[22:25]
	v_mfma_f32_16x16x32_bf16 v[14:17], v[184:187], v[208:211], v[14:17]
	v_mfma_f32_16x16x32_bf16 v[6:9], v[176:179], v[216:219], v[6:9]
	v_mfma_f32_16x16x32_bf16 v[2:5], v[184:187], v[216:219], v[2:5]
	v_mfma_f32_16x16x32_bf16 v[54:57], v[180:183], v[196:199], v[54:57]
	v_mfma_f32_16x16x32_bf16 v[46:49], v[188:191], v[196:199], v[46:49]
	v_mfma_f32_16x16x32_bf16 v[38:41], v[180:183], v[204:207], v[38:41]
	v_mfma_f32_16x16x32_bf16 v[30:33], v[188:191], v[204:207], v[30:33]
	v_mfma_f32_16x16x32_bf16 v[22:25], v[180:183], v[212:215], v[22:25]
	v_mfma_f32_16x16x32_bf16 v[14:17], v[188:191], v[212:215], v[14:17]
	v_mfma_f32_16x16x32_bf16 v[6:9], v[180:183], v[220:223], v[6:9]
	v_mfma_f32_16x16x32_bf16 v[2:5], v[188:191], v[220:223], v[2:5]
	s_setprio 0
	s_barrier
	s_add_i32 s23, s23, 2
	s_add_u32 s0, s0, 0x100
	s_addc_u32 s1, s1, 0
	s_add_u32 s13, s13, 0x100
	s_addc_u32 s22, s22, 0
	s_cmp_gt_u32 s23, 13
	s_cbranch_scc0 .LBB0_260
	s_and_b64 vcc, exec, s[20:21]
	s_cbranch_vccnz .LBB0_265
	v_lshl_add_u32 v152, s12, 8, v1
	s_cmp_gt_i32 s86, 15
	s_mov_b64 s[0:1], -1
	s_cbranch_scc1 .LBB0_266

	.amdhsa_kernel _Z6mk_fwd4Args
		.amdhsa_group_segment_fixed_size 0
		.amdhsa_private_segment_fixed_size 0
		.amdhsa_kernarg_size 472
		.amdhsa_user_sgpr_count 2
		.amdhsa_user_sgpr_dispatch_ptr 0
		.amdhsa_user_sgpr_queue_ptr 0
		.amdhsa_user_sgpr_kernarg_segment_ptr 1
		.amdhsa_user_sgpr_dispatch_id 0
		.amdhsa_user_sgpr_kernarg_preload_length 0
		.amdhsa_user_sgpr_kernarg_preload_offset 0
		.amdhsa_user_sgpr_private_segment_size 0
		.amdhsa_uses_dynamic_stack 0
		.amdhsa_enable_private_segment 0
		.amdhsa_system_sgpr_workgroup_id_x 1
		.amdhsa_system_sgpr_workgroup_id_y 0
		.amdhsa_system_sgpr_workgroup_id_z 0
		.amdhsa_system_sgpr_workgroup_info 0
		.amdhsa_system_vgpr_workitem_id 0
		.amdhsa_next_free_vgpr 246
		.amdhsa_next_free_sgpr 100
		.amdhsa_accum_offset 248
		.amdhsa_reserve_vcc 1
		.amdhsa_float_round_mode_32 0
		.amdhsa_float_round_mode_16_64 0
		.amdhsa_float_denorm_mode_32 3
		.amdhsa_float_denorm_mode_16_64 3
		.amdhsa_dx10_clamp 1
		.amdhsa_ieee_mode 1
		.amdhsa_fp16_overflow 0
		.amdhsa_tg_split 0
		.amdhsa_exception_fp_ieee_invalid_op 0
		.amdhsa_exception_fp_denorm_src 0
		.amdhsa_exception_fp_ieee_div_zero 0
		.amdhsa_exception_fp_ieee_overflow 0
		.amdhsa_exception_fp_ieee_underflow 0
		.amdhsa_exception_fp_ieee_inexact 0
		.amdhsa_exception_int_div_zero 0
	.end_amdhsa_kernel

amdhsa.kernels:
  - .agpr_count:     0
    .args:
      - .offset:         0
        .size:           216
        .value_kind:     by_value
      - .offset:         216
        .size:           4
        .value_kind:     hidden_block_count_x
      - .offset:         220
        .size:           4
        .value_kind:     hidden_block_count_y
      - .offset:         224
        .size:           4
        .value_kind:     hidden_block_count_z
      - .offset:         228
        .size:           2
        .value_kind:     hidden_group_size_x
      - .offset:         230
        .size:           2
        .value_kind:     hidden_group_size_y
      - .offset:         232
        .size:           2
        .value_kind:     hidden_group_size_z
      - .offset:         234
        .size:           2
        .value_kind:     hidden_remainder_x
      - .offset:         236
        .size:           2
        .value_kind:     hidden_remainder_y
      - .offset:         238
        .size:           2
        .value_kind:     hidden_remainder_z
      - .offset:         256
        .size:           8
        .value_kind:     hidden_global_offset_x
      - .offset:         264
        .size:           8
        .value_kind:     hidden_global_offset_y
      - .offset:         272
        .size:           8
        .value_kind:     hidden_global_offset_z
      - .offset:         280
        .size:           2
        .value_kind:     hidden_grid_dims
      - .offset:         336
        .size:           4
        .value_kind:     hidden_dynamic_lds_size
    .group_segment_fixed_size: 0
    .kernarg_segment_align: 8
    .kernarg_segment_size: 472
    .language:       OpenCL C
    .language_version:
      - 2
      - 0
    .max_flat_workgroup_size: 512
    .name:           _Z6mk_fwd4Args
    .private_segment_fixed_size: 0
    .sgpr_count:     106
    .sgpr_spill_count: 175
    .symbol:         _Z6mk_fwd4Args.kd
    .uniform_work_group_size: 1
    .uses_dynamic_stack: false
    .vgpr_count:     246
    .vgpr_spill_count: 0
    .wavefront_size: 64
